# K-loop restructured: 4 merged phases of 32 MFMAs per K-tile pair-half (8 barriers per 2 K-tiles instead of 16), B0+B1 fragments loaded together, LDS-DMA schedule re-derived (vmcnt 8/6)
# speedup vs baseline: 1.0192x; 1.0192x over previous
; __device__ __forceinline__ int otid() { int t = threadIdx.x; asm volatile("" : "+v"(t)); return t; }
; #define PG8_STAGE(bufoff, gbase, voff) do { _Pragma("unroll") for (int _i = 0; _i < 2; ++_i) \
;         __builtin_amdgcn_global_load_lds((const unsigned*)((const char*)(gbase) + (voff)[_i]), (LAS unsigned*)(lds + (bufoff) + ldsw + _i * 8192), 16, 0, 0); } while (0)
; #define PG8_WAIT_V(n) asm volatile("s_waitcnt vmcnt(" #n ")" ::: "memory")
; #define PG8_BAR __builtin_amdgcn_s_barrier()
; __device__ __forceinline__ void gemm_phase(LAS unsigned char* lds, const Gemm g, const StaticOrder& S, const Epi& E) {
;     const int tid = otid(), wid = __builtin_amdgcn_readfirstlane(tid >> 6), lane = tid & 63, wr = wid >> 2, wc = wid & 3, fr = lane & 15, fq = lane >> 4;
;     const int K = g.K, nt = K / BK;
;     unsigned voffA[2], voffB[2];
; #pragma unroll
;     for (int i = 0; i < 2; ++i) { int R, C; stage_rc(tid * 16 + i * 8192, R, C); const int Rb = (R & ~31) + perm32(R & 31);
;         voffA[i] = (unsigned)(R * K + C) * 2u; voffB[i] = (unsigned)(Rb * K + C) * 2u; }
;     const size_t kstep = (size_t)(BK * 2);
;     const size_t hstep = (size_t)HALF * K * 2;
;     const size_t tstep = 2 * hstep;
;     const unsigned ldsw = (unsigned)wid * 1024u;
;     const int aoff = lds_byte(wr * 64 + fr, fq * 8), boff = lds_byte(wc * 32 + fr, fq * 8);
;     ...
;     Unit cur, nxt; int ui = 0;
;     if (!S.next(0, cur)) return;
;     f32x4 acc[2][2][4][2];
; #pragma unroll
;     for (int a = 0; a < 2; ++a)
; #pragma unroll
;         for (int b = 0; b < 2; ++b)
; #pragma unroll
;             for (int m = 0; m < 4; ++m)
; #pragma unroll
;                 for (int n = 0; n < 2; ++n) acc[a][b][m][n] = (f32x4){0.f, 0.f, 0.f, 0.f};
;     bf16x8 At[4][2], B0[2][2], B1[2][2];
;     const char* cA = (const char*)g.A + (size_t)cur.pm * tstep; const char* cB = (const char*)g.Bt + (size_t)cur.pn * tstep;
;     PG8_STAGE(PG8_SB(0, 0), cB, voffB); PG8_STAGE(PG8_SA(0, 0), cA, voffA); PG8_STAGE(PG8_SB(0, 1), cB + hstep, voffB); PG8_STAGE(PG8_SA(0, 1), cA + hstep, voffA);
;     if (wr == 1) PG8_BAR;
;     PG8_WAIT_V(4); PG8_BAR;
;     PG8_STAGE(PG8_SB(1, 0), cB + kstep, voffB); PG8_STAGE(PG8_SA(1, 0), cA + kstep, voffA); PG8_STAGE(PG8_SB(1, 1), cB + hstep + kstep, voffB);
;     PG8_WAIT_V(6); PG8_BAR;
.LBB0_546:
	s_add_i32 m0, s66, 0x18000
	v_lshl_add_u64 v[12:13], v[12:13], 0, s[20:21]
	s_waitcnt vmcnt(0)
	s_barrier
	global_load_lds_dwordx4 v[12:13], off
	v_lshl_add_u64 v[10:11], v[10:11], 0, s[20:21]
	s_add_i32 m0, s66, 0x1a000
	s_add_i32 s70, s66, 0x8000
	global_load_lds_dwordx4 v[10:11], off
	v_lshl_add_u64 v[8:9], v[8:9], 0, s[20:21]
	s_mov_b32 m0, s70
	s_add_i32 s71, s66, 0xa000
	global_load_lds_dwordx4 v[8:9], off
	v_lshl_add_u64 v[6:7], v[6:7], 0, s[20:21]
	s_mov_b32 m0, s71
	v_lshl_add_u64 v[4:5], v[4:5], 0, s[20:21]
	global_load_lds_dwordx4 v[6:7], off
	s_add_i32 m0, s66, 0x1c000
	v_lshl_add_u64 v[2:3], v[2:3], 0, s[20:21]
	s_nop 0
	s_add_i32 m0, s66, 0x1e000
	s_and_b32 s44, s39, 3
	s_nop 0
	v_bfe_u32 v3, v0, 4, 2
	v_and_b32_e32 v2, 15, v0
	v_lshlrev_b32_e32 v5, 4, v3
	v_lshlrev_b32_e32 v0, 2, v0
	s_lshr_b32 s72, s43, 6
	v_lshl_or_b32 v243, s40, 6, v2
	v_lshl_or_b32 v2, v2, 6, v5
	s_lshl_b32 s39, s40, 13
	v_and_b32_e32 v0, 32, v0
	v_bitop3_b32 v6, v2, s39, v0 bitop3:0xde
	s_lshl_b32 s39, s44, 12
	s_add_i32 s73, s72, -2
	s_cmp_eq_u32 s44, 0
	v_lshlrev_b32_e32 v4, 3, v3
	s_cselect_b64 s[40:41], -1, 0
	v_cmp_gt_u32_e32 vcc, 2, v3
	s_lshl_b32 s77, s42, 2
	v_bitop3_b32 v244, v2, s39, v0 bitop3:0xde
	v_lshl_or_b32 v2, s44, 5, v4
	s_and_b64 s[52:53], s[40:41], vcc
	v_cmp_eq_u32_e64 s[40:41], 0, v3
	v_lshlrev_b32_e32 v4, 5, v3
	v_cvt_f32_u32_e32 v3, s77
	s_waitcnt lgkmcnt(0)
	s_ashr_i32 s75, s63, 31
	s_lshl_b32 s76, s42, 3
	s_lshl_b64 s[42:43], s[96:97], 21
	v_rcp_iflag_f32_e32 v3, v3
	v_lshlrev_b32_e32 v0, 1, v2
	s_add_u32 s42, s28, s42
	v_lshl_add_u64 v[188:189], s[26:27], 0, v[0:1]
	s_addc_u32 s43, s29, s43
	v_lshl_add_u64 v[194:195], s[28:29], 0, v[0:1]
	v_mul_f32_e32 v0, 0x4f7ffffe, v3
	s_add_u32 s42, s42, 0x26900000
	v_cvt_u32_f32_e32 v0, v0
	s_addc_u32 s43, s43, 0
	v_mov_b32_e32 v234, s42
	v_mov_b32_e32 v235, s43
	v_mov_b32_e32 v241, -1
	v_mov_b32_e32 v5, v1
	v_lshl_add_u64 v[190:191], s[42:43], 0, v[4:5]
	v_lshl_add_u64 v[4:5], s[28:29], 0, v[4:5]
	s_mov_b64 s[28:29], 0x22900000
	v_lshl_add_u64 v[196:197], v[194:195], 0, s[28:29]
	s_lshl_b32 s28, s44, 2
	s_add_u32 s78, s42, s28
	v_readfirstlane_b32 s29, v0
	v_add_u32_e32 v0, v16, v14
	s_addc_u32 s79, s43, 0
	s_sub_i32 s28, 0, s77
	v_add_lshl_u32 v0, v0, v15, 1
	s_waitcnt vmcnt(4)
	s_mul_i32 s28, s28, s29
	v_lshl_add_u64 v[198:199], s[48:49], 0, v[0:1]
	v_add_u32_e32 v0, v19, v17
	s_mov_b64 s[46:47], 0x34700000
	s_mul_hi_u32 s28, s29, s28
	v_add_lshl_u32 v0, v0, v18, 1
	s_mov_b32 s74, 0
	s_mov_b32 s39, s97
	v_lshl_add_u64 v[192:193], v[4:5], 0, s[46:47]
	s_add_i32 s80, s29, s28
	v_lshl_add_u64 v[200:201], s[48:49], 0, v[0:1]
	v_add_u32_e32 v245, 0, v6
	v_lshlrev_b32_e32 v0, 1, v2
	v_readlane_b32 s85, v254, 63
	s_barrier
	s_branch .LBB0_548

; #define PG8_STAGE(bufoff, gbase, voff) do { _Pragma("unroll") for (int _i = 0; _i < 2; ++_i) \
;         __builtin_amdgcn_global_load_lds((const unsigned*)((const char*)(gbase) + (voff)[_i]), (LAS unsigned*)(lds + (bufoff) + ldsw + _i * 8192), 16, 0, 0); } while (0)
; #define PG8_LDA(dst, b, h) do { _Pragma("unroll") for (int m = 0; m < 4; ++m) _Pragma("unroll") for (int k = 0; k < 2; ++k) dst[m][k] = *(const LAS bf16x8*)(lds + PG8_SA(b, h) + aoff + m * 2048 + k * 1024); } while (0)
; #define PG8_LDB(dst, b, h) do { _Pragma("unroll") for (int n = 0; n < 2; ++n) _Pragma("unroll") for (int k = 0; k < 2; ++k) dst[n][k] = *(const LAS bf16x8*)(lds + PG8_SB(b, h) + boff + n * 2048 + k * 1024); } while (0)
; #define PG8_MMA(ai, bj, At, Bt) do { __builtin_amdgcn_s_setprio(1); _Pragma("unroll") for (int m = 0; m < 4; ++m) _Pragma("unroll") for (int n = 0; n < 2; ++n) _Pragma("unroll") for (int k = 0; k < 2; ++k) \
;         acc[ai][bj][m][n] = __builtin_amdgcn_mfma_f32_16x16x32_bf16(Bt[n][k], At[m][k], acc[ai][bj][m][n], 0, 0, 0); __builtin_amdgcn_s_setprio(0); } while (0)
; #define PG8_WAIT_V(n) asm volatile("s_waitcnt vmcnt(" #n ")" ::: "memory")
; #define PG8_WAIT_L(n) asm volatile("s_waitcnt lgkmcnt(" #n ")" ::: "memory")
; #define PG8_BAR __builtin_amdgcn_s_barrier()
; __device__ __forceinline__ void gemm_phase(LAS unsigned char* lds, const Gemm g, const StaticOrder& S, const Epi& E) {
;     ...
;         for (int t = 0; t < nt; t += 2) {
;             const bool last = (t == nt - 2);
;             const char* a1 = cA + (size_t)(t + 1) * kstep;
;             const char* a2 = last ? nA : cA + (size_t)(t + 2) * kstep; const char* b2 = last ? nB : cB + (size_t)(t + 2) * kstep;
;             const char* a3 = a2 + kstep; const char* b3 = b2 + kstep;
;             PG8_LDB(B0, 0, 0); PG8_SCHED; PG8_LDA(At, 0, 0); PG8_STAGE(PG8_SA(1, 1), a1 + hstep, voffA);
;             PG8_WAIT_L(8); PG8_BAR; PG8_WAIT_L(0); PG8_MMA(0, 0, At, B0); PG8_BAR; PG8_SCHED;
;             PG8_LDB(B1, 0, 1); PG8_STAGE(PG8_SB(0, 0), b2, voffB);
;             PG8_BAR; PG8_WAIT_L(0); PG8_MMA(0, 1, At, B1); PG8_BAR;
;             PG8_LDA(At, 0, 1); PG8_STAGE(PG8_SA(0, 0), a2, voffA);
;             PG8_BAR; PG8_WAIT_L(0); PG8_MMA(1, 0, At, B0); PG8_BAR; PG8_SCHED;
;             PG8_STAGE(PG8_SB(0, 1), b2 + hstep, voffB);
;             PG8_WAIT_V(6); PG8_BAR; PG8_MMA(1, 1, At, B1); PG8_BAR;
.LBB0_555:
	s_add_i32 s61, s54, 2
	s_add_u32 s56, s44, 0x80
	s_addc_u32 s55, s45, 0
	v_add_u32_e32 v142, 0x10000, v244
	v_add_u32_e32 v178, 0x14000, v244
	s_waitcnt lgkmcnt(0)
	ds_read_b128 v[130:133], v142
	ds_read_b128 v[134:137], v142 offset:1024
	ds_read_b128 v[138:141], v142 offset:2048
	ds_read_b128 v[142:145], v142 offset:3072
	ds_read_b128 v[202:205], v178
	ds_read_b128 v[206:209], v178 offset:1024
	ds_read_b128 v[210:213], v178 offset:2048
	ds_read_b128 v[214:217], v178 offset:3072
	s_cmp_eq_u32 s73, s54
	s_cselect_b32 s54, s28, s56
	s_cselect_b32 s55, s29, s55
	s_cselect_b32 s57, s47, s60
	s_cselect_b32 s56, s46, s59
	s_waitcnt lgkmcnt(4)
	ds_read_b128 v[146:149], v245
	ds_read_b128 v[150:153], v245 offset:1024
	ds_read_b128 v[154:157], v245 offset:2048
	ds_read_b128 v[158:161], v245 offset:3072
	ds_read_b128 v[162:165], v245 offset:4096
	ds_read_b128 v[166:169], v245 offset:5120
	ds_read_b128 v[170:173], v245 offset:6144
	ds_read_b128 v[174:177], v245 offset:7168
	s_add_u32 s86, s59, s48
	s_addc_u32 s87, s60, 0
	s_sub_u32 s86, s86, 0x80
	s_subb_u32 s87, s87, 0
	v_lshl_add_u64 v[246:247], s[86:87], 0, v[182:183]
	s_add_i32 m0, s65, 0x1c000
	s_nop 0
	global_load_lds_dwordx4 v[246:247], off
	v_lshl_add_u64 v[246:247], s[86:87], 0, v[186:187]
	s_add_i32 m0, s65, 0x1e000
	s_nop 0
	global_load_lds_dwordx4 v[246:247], off
	v_lshl_add_u64 v[248:249], s[44:45], 0, v[198:199]
	s_add_i32 m0, s66, 0xc000
	s_nop 0
	global_load_lds_dwordx4 v[248:249], off
	v_lshl_add_u64 v[248:249], s[44:45], 0, v[200:201]
	s_add_i32 m0, s66, 0xe000
	s_nop 0
	global_load_lds_dwordx4 v[248:249], off
	s_cmp_eq_u32 s61, 2
	s_cbranch_scc1 .Lmy_q10_first
	s_waitcnt vmcnt(8)
.Lmy_q10_first:
	s_waitcnt lgkmcnt(0)
	s_barrier
	s_setprio 1
	v_mfma_f32_16x16x32_bf16 v[126:129], v[130:133], v[146:149], v[126:129]
	v_mfma_f32_16x16x32_bf16 v[122:125], v[138:141], v[146:149], v[122:125]
	v_mfma_f32_16x16x32_bf16 v[118:121], v[130:133], v[154:157], v[118:121]
	v_mfma_f32_16x16x32_bf16 v[110:113], v[138:141], v[154:157], v[110:113]
	v_mfma_f32_16x16x32_bf16 v[102:105], v[130:133], v[162:165], v[102:105]
	v_mfma_f32_16x16x32_bf16 v[94:97], v[138:141], v[162:165], v[94:97]
	v_mfma_f32_16x16x32_bf16 v[86:89], v[130:133], v[170:173], v[86:89]
	v_mfma_f32_16x16x32_bf16 v[78:81], v[138:141], v[170:173], v[78:81]
	v_mfma_f32_16x16x32_bf16 v[126:129], v[134:137], v[150:153], v[126:129]
	v_mfma_f32_16x16x32_bf16 v[122:125], v[142:145], v[150:153], v[122:125]
	v_mfma_f32_16x16x32_bf16 v[118:121], v[134:137], v[158:161], v[118:121]
	v_mfma_f32_16x16x32_bf16 v[110:113], v[142:145], v[158:161], v[110:113]
	v_mfma_f32_16x16x32_bf16 v[102:105], v[134:137], v[166:169], v[102:105]
	v_mfma_f32_16x16x32_bf16 v[94:97], v[142:145], v[166:169], v[94:97]
	v_mfma_f32_16x16x32_bf16 v[86:89], v[134:137], v[174:177], v[86:89]
	v_mfma_f32_16x16x32_bf16 v[78:81], v[142:145], v[174:177], v[78:81]
	v_mfma_f32_16x16x32_bf16 v[114:117], v[202:205], v[146:149], v[114:117]
	v_mfma_f32_16x16x32_bf16 v[106:109], v[210:213], v[146:149], v[106:109]
	v_mfma_f32_16x16x32_bf16 v[98:101], v[202:205], v[154:157], v[98:101]
	v_mfma_f32_16x16x32_bf16 v[90:93], v[210:213], v[154:157], v[90:93]
	v_mfma_f32_16x16x32_bf16 v[82:85], v[202:205], v[162:165], v[82:85]
	v_mfma_f32_16x16x32_bf16 v[74:77], v[210:213], v[162:165], v[74:77]
	v_mfma_f32_16x16x32_bf16 v[70:73], v[202:205], v[170:173], v[70:73]
	v_mfma_f32_16x16x32_bf16 v[66:69], v[210:213], v[170:173], v[66:69]
	v_mfma_f32_16x16x32_bf16 v[114:117], v[206:209], v[150:153], v[114:117]
	v_mfma_f32_16x16x32_bf16 v[106:109], v[214:217], v[150:153], v[106:109]
	v_mfma_f32_16x16x32_bf16 v[98:101], v[206:209], v[158:161], v[98:101]
	v_mfma_f32_16x16x32_bf16 v[90:93], v[214:217], v[158:161], v[90:93]
	v_mfma_f32_16x16x32_bf16 v[82:85], v[206:209], v[166:169], v[82:85]
	v_mfma_f32_16x16x32_bf16 v[74:77], v[214:217], v[166:169], v[74:77]
	v_mfma_f32_16x16x32_bf16 v[70:73], v[206:209], v[174:177], v[70:73]
	v_mfma_f32_16x16x32_bf16 v[66:69], v[214:217], v[174:177], v[66:69]
	s_setprio 0
	s_barrier
	ds_read_b128 v[146:149], v245 offset:16384
	ds_read_b128 v[150:153], v245 offset:17408
	ds_read_b128 v[154:157], v245 offset:18432
	ds_read_b128 v[158:161], v245 offset:19456
	ds_read_b128 v[162:165], v245 offset:20480
	ds_read_b128 v[166:169], v245 offset:21504
	ds_read_b128 v[170:173], v245 offset:22528
	ds_read_b128 v[174:177], v245 offset:23552
	s_add_u32 s86, s56, 0x80
	s_addc_u32 s87, s57, 0
	s_add_u32 s88, s54, 0x80
	s_addc_u32 s89, s55, 0
	v_lshl_add_u64 v[246:247], s[56:57], 0, v[182:183]
	s_add_i32 m0, s65, 0x10000
	s_nop 0
	global_load_lds_dwordx4 v[246:247], off
	v_lshl_add_u64 v[246:247], s[56:57], 0, v[186:187]
	s_add_i32 m0, s65, 0x12000
	s_nop 0
	global_load_lds_dwordx4 v[246:247], off
	v_lshl_add_u64 v[248:249], s[54:55], 0, v[180:181]
	s_mov_b32 m0, s66
	s_nop 0
	global_load_lds_dwordx4 v[248:249], off
	v_lshl_add_u64 v[248:249], s[54:55], 0, v[184:185]
	s_mov_b32 m0, s67
	s_nop 0
	global_load_lds_dwordx4 v[248:249], off
	s_waitcnt vmcnt(6) lgkmcnt(0)
	s_barrier
; #define PG8_STAGE(bufoff, gbase, voff) do { _Pragma("unroll") for (int _i = 0; _i < 2; ++_i) \
;         __builtin_amdgcn_global_load_lds((const unsigned*)((const char*)(gbase) + (voff)[_i]), (LAS unsigned*)(lds + (bufoff) + ldsw + _i * 8192), 16, 0, 0); } while (0)
; #define PG8_LDA(dst, b, h) do { _Pragma("unroll") for (int m = 0; m < 4; ++m) _Pragma("unroll") for (int k = 0; k < 2; ++k) dst[m][k] = *(const LAS bf16x8*)(lds + PG8_SA(b, h) + aoff + m * 2048 + k * 1024); } while (0)
; #define PG8_LDB(dst, b, h) do { _Pragma("unroll") for (int n = 0; n < 2; ++n) _Pragma("unroll") for (int k = 0; k < 2; ++k) dst[n][k] = *(const LAS bf16x8*)(lds + PG8_SB(b, h) + boff + n * 2048 + k * 1024); } while (0)
; #define PG8_MMA(ai, bj, At, Bt) do { __builtin_amdgcn_s_setprio(1); _Pragma("unroll") for (int m = 0; m < 4; ++m) _Pragma("unroll") for (int n = 0; n < 2; ++n) _Pragma("unroll") for (int k = 0; k < 2; ++k) \
;         acc[ai][bj][m][n] = __builtin_amdgcn_mfma_f32_16x16x32_bf16(Bt[n][k], At[m][k], acc[ai][bj][m][n], 0, 0, 0); __builtin_amdgcn_s_setprio(0); } while (0)
; #define PG8_BAR __builtin_amdgcn_s_barrier()
; __device__ __forceinline__ void gemm_phase(LAS unsigned char* lds, const Gemm g, const StaticOrder& S, const Epi& E) {
;     ...
;             PG8_WAIT_L(8); PG8_BAR; PG8_WAIT_L(0); PG8_MMA(0, 0, At, B0); PG8_BAR; PG8_SCHED;
;             PG8_LDB(B1, 0, 1); PG8_STAGE(PG8_SB(0, 0), b2, voffB);
;             PG8_BAR; PG8_WAIT_L(0); PG8_MMA(0, 1, At, B1); PG8_BAR;
;             PG8_LDA(At, 0, 1); PG8_STAGE(PG8_SA(0, 0), a2, voffA);
;             PG8_BAR; PG8_WAIT_L(0); PG8_MMA(1, 0, At, B0); PG8_BAR; PG8_SCHED;
;             PG8_STAGE(PG8_SB(0, 1), b2 + hstep, voffB);
;             PG8_WAIT_V(6); PG8_BAR; PG8_MMA(1, 1, At, B1); PG8_BAR;
;             PG8_LDB(B0, 1, 0); PG8_SCHED; PG8_LDA(At, 1, 0); PG8_STAGE(PG8_SA(0, 1), a2 + hstep, voffA);
;             PG8_WAIT_L(8); PG8_BAR; PG8_WAIT_L(0); PG8_MMA(0, 0, At, B0); PG8_BAR; PG8_SCHED;
;             PG8_LDB(B1, 1, 1); PG8_STAGE(PG8_SB(1, 0), b3, voffB);
;             PG8_BAR; PG8_WAIT_L(0); PG8_MMA(0, 1, At, B1); PG8_BAR;
;             PG8_LDA(At, 1, 1); PG8_STAGE(PG8_SA(1, 0), a3, voffA);
;             PG8_BAR; PG8_WAIT_L(0); PG8_MMA(1, 0, At, B0); PG8_BAR; PG8_SCHED;
;             PG8_STAGE(PG8_SB(1, 1), b3 + hstep, voffB);
;             PG8_WAIT_V(6); PG8_BAR; PG8_MMA(1, 1, At, B1); PG8_BAR;
	s_setprio 1
	v_mfma_f32_16x16x32_bf16 v[62:65], v[130:133], v[146:149], v[62:65]
	v_mfma_f32_16x16x32_bf16 v[58:61], v[138:141], v[146:149], v[58:61]
	v_mfma_f32_16x16x32_bf16 v[54:57], v[130:133], v[154:157], v[54:57]
	v_mfma_f32_16x16x32_bf16 v[50:53], v[138:141], v[154:157], v[50:53]
	v_mfma_f32_16x16x32_bf16 v[38:41], v[130:133], v[162:165], v[38:41]
	v_mfma_f32_16x16x32_bf16 v[34:37], v[138:141], v[162:165], v[34:37]
	v_mfma_f32_16x16x32_bf16 v[22:25], v[130:133], v[170:173], v[22:25]
	v_mfma_f32_16x16x32_bf16 v[18:21], v[138:141], v[170:173], v[18:21]
	v_mfma_f32_16x16x32_bf16 v[62:65], v[134:137], v[150:153], v[62:65]
	v_mfma_f32_16x16x32_bf16 v[58:61], v[142:145], v[150:153], v[58:61]
	v_mfma_f32_16x16x32_bf16 v[54:57], v[134:137], v[158:161], v[54:57]
	v_mfma_f32_16x16x32_bf16 v[50:53], v[142:145], v[158:161], v[50:53]
	v_mfma_f32_16x16x32_bf16 v[38:41], v[134:137], v[166:169], v[38:41]
	v_mfma_f32_16x16x32_bf16 v[34:37], v[142:145], v[166:169], v[34:37]
	v_mfma_f32_16x16x32_bf16 v[22:25], v[134:137], v[174:177], v[22:25]
	v_mfma_f32_16x16x32_bf16 v[18:21], v[142:145], v[174:177], v[18:21]
	v_mfma_f32_16x16x32_bf16 v[46:49], v[202:205], v[146:149], v[46:49]
	v_mfma_f32_16x16x32_bf16 v[42:45], v[210:213], v[146:149], v[42:45]
	v_mfma_f32_16x16x32_bf16 v[30:33], v[202:205], v[154:157], v[30:33]
	v_mfma_f32_16x16x32_bf16 v[26:29], v[210:213], v[154:157], v[26:29]
	v_mfma_f32_16x16x32_bf16 v[14:17], v[202:205], v[162:165], v[14:17]
	v_mfma_f32_16x16x32_bf16 v[10:13], v[210:213], v[162:165], v[10:13]
	v_mfma_f32_16x16x32_bf16 v[6:9], v[202:205], v[170:173], v[6:9]
	v_mfma_f32_16x16x32_bf16 v[2:5], v[210:213], v[170:173], v[2:5]
	v_mfma_f32_16x16x32_bf16 v[46:49], v[206:209], v[150:153], v[46:49]
	v_mfma_f32_16x16x32_bf16 v[42:45], v[214:217], v[150:153], v[42:45]
	v_mfma_f32_16x16x32_bf16 v[30:33], v[206:209], v[158:161], v[30:33]
	v_mfma_f32_16x16x32_bf16 v[26:29], v[214:217], v[158:161], v[26:29]
	v_mfma_f32_16x16x32_bf16 v[14:17], v[206:209], v[166:169], v[14:17]
	v_mfma_f32_16x16x32_bf16 v[10:13], v[214:217], v[166:169], v[10:13]
	v_mfma_f32_16x16x32_bf16 v[6:9], v[206:209], v[174:177], v[6:9]
	v_mfma_f32_16x16x32_bf16 v[2:5], v[214:217], v[174:177], v[2:5]
	s_setprio 0
	s_barrier
	v_add_u32_e32 v142, 0x18000, v244
	v_add_u32_e32 v178, 0x1c000, v244
	ds_read_b128 v[130:133], v142
	ds_read_b128 v[134:137], v142 offset:1024
	ds_read_b128 v[138:141], v142 offset:2048
	ds_read_b128 v[142:145], v142 offset:3072
	ds_read_b128 v[202:205], v178
	ds_read_b128 v[206:209], v178 offset:1024
	ds_read_b128 v[210:213], v178 offset:2048
	ds_read_b128 v[214:217], v178 offset:3072
	s_waitcnt lgkmcnt(4)
	ds_read_b128 v[146:149], v245 offset:32768
	ds_read_b128 v[150:153], v245 offset:33792
	ds_read_b128 v[154:157], v245 offset:34816
	ds_read_b128 v[158:161], v245 offset:35840
	ds_read_b128 v[162:165], v245 offset:36864
	ds_read_b128 v[166:169], v245 offset:37888
	ds_read_b128 v[170:173], v245 offset:38912
	ds_read_b128 v[174:177], v245 offset:39936
	s_add_u32 s56, s56, s48
	s_addc_u32 s57, s57, 0
	s_add_u32 s54, s54, s48
	s_addc_u32 s55, s55, 0
	v_lshl_add_u64 v[246:247], s[56:57], 0, v[182:183]
	s_add_i32 m0, s65, 0x14000
	s_nop 0
	global_load_lds_dwordx4 v[246:247], off
	v_lshl_add_u64 v[246:247], s[56:57], 0, v[186:187]
	s_add_i32 m0, s65, 0x16000
	s_nop 0
	global_load_lds_dwordx4 v[246:247], off
	v_lshl_add_u64 v[248:249], s[54:55], 0, v[180:181]
	s_mov_b32 m0, s68
	s_nop 0
	global_load_lds_dwordx4 v[248:249], off
	v_lshl_add_u64 v[248:249], s[54:55], 0, v[184:185]
	s_mov_b32 m0, s69
	s_nop 0
	global_load_lds_dwordx4 v[248:249], off
	s_waitcnt vmcnt(8) lgkmcnt(0)
	s_barrier
	s_setprio 1
	v_mfma_f32_16x16x32_bf16 v[126:129], v[130:133], v[146:149], v[126:129]
	v_mfma_f32_16x16x32_bf16 v[122:125], v[138:141], v[146:149], v[122:125]
	v_mfma_f32_16x16x32_bf16 v[118:121], v[130:133], v[154:157], v[118:121]
	v_mfma_f32_16x16x32_bf16 v[110:113], v[138:141], v[154:157], v[110:113]
	v_mfma_f32_16x16x32_bf16 v[102:105], v[130:133], v[162:165], v[102:105]
	v_mfma_f32_16x16x32_bf16 v[94:97], v[138:141], v[162:165], v[94:97]
	v_mfma_f32_16x16x32_bf16 v[86:89], v[130:133], v[170:173], v[86:89]
	v_mfma_f32_16x16x32_bf16 v[78:81], v[138:141], v[170:173], v[78:81]
	v_mfma_f32_16x16x32_bf16 v[126:129], v[134:137], v[150:153], v[126:129]
	v_mfma_f32_16x16x32_bf16 v[122:125], v[142:145], v[150:153], v[122:125]
	v_mfma_f32_16x16x32_bf16 v[118:121], v[134:137], v[158:161], v[118:121]
	v_mfma_f32_16x16x32_bf16 v[110:113], v[142:145], v[158:161], v[110:113]
	v_mfma_f32_16x16x32_bf16 v[102:105], v[134:137], v[166:169], v[102:105]
	v_mfma_f32_16x16x32_bf16 v[94:97], v[142:145], v[166:169], v[94:97]
	v_mfma_f32_16x16x32_bf16 v[86:89], v[134:137], v[174:177], v[86:89]
	v_mfma_f32_16x16x32_bf16 v[78:81], v[142:145], v[174:177], v[78:81]
	v_mfma_f32_16x16x32_bf16 v[114:117], v[202:205], v[146:149], v[114:117]
	v_mfma_f32_16x16x32_bf16 v[106:109], v[210:213], v[146:149], v[106:109]
	v_mfma_f32_16x16x32_bf16 v[98:101], v[202:205], v[154:157], v[98:101]
	v_mfma_f32_16x16x32_bf16 v[90:93], v[210:213], v[154:157], v[90:93]
	v_mfma_f32_16x16x32_bf16 v[82:85], v[202:205], v[162:165], v[82:85]
	v_mfma_f32_16x16x32_bf16 v[74:77], v[210:213], v[162:165], v[74:77]
	v_mfma_f32_16x16x32_bf16 v[70:73], v[202:205], v[170:173], v[70:73]
	v_mfma_f32_16x16x32_bf16 v[66:69], v[210:213], v[170:173], v[66:69]
	v_mfma_f32_16x16x32_bf16 v[114:117], v[206:209], v[150:153], v[114:117]
	v_mfma_f32_16x16x32_bf16 v[106:109], v[214:217], v[150:153], v[106:109]
	v_mfma_f32_16x16x32_bf16 v[98:101], v[206:209], v[158:161], v[98:101]
	v_mfma_f32_16x16x32_bf16 v[90:93], v[214:217], v[158:161], v[90:93]
	v_mfma_f32_16x16x32_bf16 v[82:85], v[206:209], v[166:169], v[82:85]
	v_mfma_f32_16x16x32_bf16 v[74:77], v[214:217], v[166:169], v[74:77]
	v_mfma_f32_16x16x32_bf16 v[70:73], v[206:209], v[174:177], v[70:73]
	v_mfma_f32_16x16x32_bf16 v[66:69], v[214:217], v[174:177], v[66:69]
	s_setprio 0
	s_barrier
	ds_read_b128 v[146:149], v245 offset:49152
	ds_read_b128 v[150:153], v245 offset:50176
	ds_read_b128 v[154:157], v245 offset:51200
	ds_read_b128 v[158:161], v245 offset:52224
	ds_read_b128 v[162:165], v245 offset:53248
	ds_read_b128 v[166:169], v245 offset:54272
	ds_read_b128 v[170:173], v245 offset:55296
	ds_read_b128 v[174:177], v245 offset:56320
	v_lshl_add_u64 v[246:247], s[86:87], 0, v[182:183]
	s_add_i32 m0, s65, 0x18000
	s_nop 0
	global_load_lds_dwordx4 v[246:247], off
	v_lshl_add_u64 v[246:247], s[86:87], 0, v[186:187]
	s_add_i32 m0, s65, 0x1a000
	s_nop 0
	global_load_lds_dwordx4 v[246:247], off
	v_lshl_add_u64 v[248:249], s[88:89], 0, v[180:181]
	s_mov_b32 m0, s70
	s_nop 0
	global_load_lds_dwordx4 v[248:249], off
	v_lshl_add_u64 v[248:249], s[88:89], 0, v[184:185]
	s_mov_b32 m0, s71
	s_nop 0
	global_load_lds_dwordx4 v[248:249], off
	s_cmp_ge_u32 s61, s72
	s_cbranch_scc1 .Lmy_q21_last
	s_waitcnt vmcnt(6)
	s_branch .Lmy_q21_cont
; #define PG8_STAGE(bufoff, gbase, voff) do { _Pragma("unroll") for (int _i = 0; _i < 2; ++_i) \
;         __builtin_amdgcn_global_load_lds((const unsigned*)((const char*)(gbase) + (voff)[_i]), (LAS unsigned*)(lds + (bufoff) + ldsw + _i * 8192), 16, 0, 0); } while (0)
; #define PG8_LDA(dst, b, h) do { _Pragma("unroll") for (int m = 0; m < 4; ++m) _Pragma("unroll") for (int k = 0; k < 2; ++k) dst[m][k] = *(const LAS bf16x8*)(lds + PG8_SA(b, h) + aoff + m * 2048 + k * 1024); } while (0)
; #define PG8_MMA(ai, bj, At, Bt) do { __builtin_amdgcn_s_setprio(1); _Pragma("unroll") for (int m = 0; m < 4; ++m) _Pragma("unroll") for (int n = 0; n < 2; ++n) _Pragma("unroll") for (int k = 0; k < 2; ++k) \
;         acc[ai][bj][m][n] = __builtin_amdgcn_mfma_f32_16x16x32_bf16(Bt[n][k], At[m][k], acc[ai][bj][m][n], 0, 0, 0); __builtin_amdgcn_s_setprio(0); } while (0)
; #define PG8_WAIT_V(n) asm volatile("s_waitcnt vmcnt(" #n ")" ::: "memory")
; #define PG8_WAIT_L(n) asm volatile("s_waitcnt lgkmcnt(" #n ")" ::: "memory")
; #define PG8_BAR __builtin_amdgcn_s_barrier()
; #define PG8_SCHED __builtin_amdgcn_sched_barrier(0)
; __device__ __forceinline__ void gemm_phase(LAS unsigned char* lds, const Gemm g, const StaticOrder& S, const Epi& E) {
;     ...
;             PG8_LDA(At, 1, 1); PG8_STAGE(PG8_SA(1, 0), a3, voffA);
;             PG8_BAR; PG8_WAIT_L(0); PG8_MMA(1, 0, At, B0); PG8_BAR; PG8_SCHED;
;             PG8_STAGE(PG8_SB(1, 1), b3 + hstep, voffB);
;             PG8_WAIT_V(6); PG8_BAR; PG8_MMA(1, 1, At, B1); PG8_BAR;
;         }
.Lmy_q21_last:
	s_waitcnt vmcnt(4)
.Lmy_q21_cont:
	s_waitcnt lgkmcnt(0)
	s_barrier
	s_setprio 1
	v_mfma_f32_16x16x32_bf16 v[62:65], v[130:133], v[146:149], v[62:65]
	v_mfma_f32_16x16x32_bf16 v[58:61], v[138:141], v[146:149], v[58:61]
	v_mfma_f32_16x16x32_bf16 v[54:57], v[130:133], v[154:157], v[54:57]
	v_mfma_f32_16x16x32_bf16 v[50:53], v[138:141], v[154:157], v[50:53]
	v_mfma_f32_16x16x32_bf16 v[38:41], v[130:133], v[162:165], v[38:41]
	v_mfma_f32_16x16x32_bf16 v[34:37], v[138:141], v[162:165], v[34:37]
	v_mfma_f32_16x16x32_bf16 v[22:25], v[130:133], v[170:173], v[22:25]
	v_mfma_f32_16x16x32_bf16 v[18:21], v[138:141], v[170:173], v[18:21]
	v_mfma_f32_16x16x32_bf16 v[62:65], v[134:137], v[150:153], v[62:65]
	v_mfma_f32_16x16x32_bf16 v[58:61], v[142:145], v[150:153], v[58:61]
	v_mfma_f32_16x16x32_bf16 v[54:57], v[134:137], v[158:161], v[54:57]
	v_mfma_f32_16x16x32_bf16 v[50:53], v[142:145], v[158:161], v[50:53]
	v_mfma_f32_16x16x32_bf16 v[38:41], v[134:137], v[166:169], v[38:41]
	v_mfma_f32_16x16x32_bf16 v[34:37], v[142:145], v[166:169], v[34:37]
	v_mfma_f32_16x16x32_bf16 v[22:25], v[134:137], v[174:177], v[22:25]
	v_mfma_f32_16x16x32_bf16 v[18:21], v[142:145], v[174:177], v[18:21]
	v_mfma_f32_16x16x32_bf16 v[46:49], v[202:205], v[146:149], v[46:49]
	v_mfma_f32_16x16x32_bf16 v[42:45], v[210:213], v[146:149], v[42:45]
	v_mfma_f32_16x16x32_bf16 v[30:33], v[202:205], v[154:157], v[30:33]
	v_mfma_f32_16x16x32_bf16 v[26:29], v[210:213], v[154:157], v[26:29]
	v_mfma_f32_16x16x32_bf16 v[14:17], v[202:205], v[162:165], v[14:17]
	v_mfma_f32_16x16x32_bf16 v[10:13], v[210:213], v[162:165], v[10:13]
	v_mfma_f32_16x16x32_bf16 v[6:9], v[202:205], v[170:173], v[6:9]
	v_mfma_f32_16x16x32_bf16 v[2:5], v[210:213], v[170:173], v[2:5]
	v_mfma_f32_16x16x32_bf16 v[46:49], v[206:209], v[150:153], v[46:49]
	v_mfma_f32_16x16x32_bf16 v[42:45], v[214:217], v[150:153], v[42:45]
	v_mfma_f32_16x16x32_bf16 v[30:33], v[206:209], v[158:161], v[30:33]
	v_mfma_f32_16x16x32_bf16 v[26:29], v[214:217], v[158:161], v[26:29]
	v_mfma_f32_16x16x32_bf16 v[14:17], v[206:209], v[166:169], v[14:17]
	v_mfma_f32_16x16x32_bf16 v[10:13], v[214:217], v[166:169], v[10:13]
	v_mfma_f32_16x16x32_bf16 v[6:9], v[206:209], v[174:177], v[6:9]
	v_mfma_f32_16x16x32_bf16 v[2:5], v[214:217], v[174:177], v[2:5]
	s_setprio 0
	s_add_u32 s44, s44, 0x100
	s_addc_u32 s45, s45, 0
	s_add_u32 s59, s59, 0x100
	s_addc_u32 s60, s60, 0
	s_cmp_ge_u32 s61, s72
	s_mov_b32 s54, s61
	s_barrier
	s_cbranch_scc0 .LBB0_555
	s_cmpk_gt_u32 s64, 0xff
	s_cbranch_scc1 .Lmy_e1
	s_barrier
